# sample-row LayerNorm (4 phases): 64-lane sums via DPP adds + row_bcast + readlane instead of 6-stage ds_bpermute butterflies
# speedup vs baseline: 1.0358x; 1.0001x over previous
; __device__ __forceinline__ f32x4 unpack4(u32x2 u) { return (f32x4){__uint_as_float(u.x << 16), __uint_as_float(u.x & 0xffff0000u), __uint_as_float(u.y << 16), __uint_as_float(u.y & 0xffff0000u)}; }
; __device__ __forceinline__ u32x2 pack4(f32x4 v) { u32x2 r; r.x = cvt_pk_bf16(v.x, v.y); r.y = cvt_pk_bf16(v.z, v.w); return r; }
; __device__ __forceinline__ float wave_sum(float v) {
; #pragma unroll
;     for (int o = 1; o < 64; o <<= 1) v += __shfl_xor(v, o);
;     return v;
; }
; __device__ __forceinline__ void ln_pass(const bf16_t* PRE, const float* g, const float* b, float* Hf, bf16_t* HB, int gw, int ngw, int lane, int row_end = MT) {
;     ...
;         f32x4 v[4]; float s = 0.f;
; #pragma unroll
;         for (int j = 0; j < 4; ++j) { v[j] = unpack4(q[j]); s += (v[j].x + v[j].y) + (v[j].z + v[j].w); }
;         const float mean = wave_sum(s) * (1.f / D); float s2 = 0.f;
; #pragma unroll
;         for (int j = 0; j < 4; ++j) { v[j] = v[j] - mean; s2 += (v[j].x * v[j].x + v[j].y * v[j].y) + (v[j].z * v[j].z + v[j].w * v[j].w); }
;         const float rstd = 1.0f / sqrtf(wave_sum(s2) * (1.f / D) + LN_EPS);
; #pragma unroll
;         for (int j = 0; j < 4; ++j) { const f32x4 o = v[j] * rstd * gv[j] + bv[j];
;             if (Hf) *(f32x4*)(Hf + (size_t)row * D + 256 * j + 4 * lane) = o;
;             if (HB) *(u32x2*)(HB + (size_t)row * D + 256 * j + 4 * lane) = pack4(o); }
.LBB0_442:
	s_waitcnt vmcnt(3)
	v_lshlrev_b32_e32 v59, 16, v49
	v_lshlrev_b32_e32 v58, 16, v48
	v_and_b32_e32 v49, 0xffff0000, v49
	v_and_b32_e32 v48, 0xffff0000, v48
	s_waitcnt vmcnt(2)
	v_lshlrev_b32_e32 v63, 16, v47
	v_lshlrev_b32_e32 v62, 16, v46
	v_and_b32_e32 v47, 0xffff0000, v47
	v_and_b32_e32 v46, 0xffff0000, v46
	v_pk_add_f32 v[60:61], v[58:59], v[48:49]
	v_pk_add_f32 v[64:65], v[62:63], v[46:47]
	v_add_f32_e32 v60, v60, v61
	v_pk_add_f32 v[64:65], v[64:65], v[64:65] op_sel_hi:[0,1]
	s_waitcnt vmcnt(1)
	v_lshlrev_b32_e32 v66, 16, v44
	v_and_b32_e32 v67, 0xffff0000, v44
	v_lshlrev_b32_e32 v44, 16, v45
	v_and_b32_e32 v45, 0xffff0000, v45
	v_add_f32_e32 v61, 0, v60
	v_add_f32_e32 v69, v66, v67
	v_add_f32_e32 v71, v44, v45
	s_waitcnt vmcnt(0)
	v_lshlrev_b32_e32 v68, 16, v42
	v_and_b32_e32 v70, 0xffff0000, v42
	v_lshlrev_b32_e32 v64, 16, v43
	v_and_b32_e32 v60, 0xffff0000, v43
	v_pk_add_f32 v[42:43], v[68:69], v[70:71]
	v_pk_add_f32 v[72:73], v[64:65], v[60:61]
	s_nop 0
	v_pk_add_f32 v[42:43], v[42:43], v[72:73]
	s_nop 0
	v_add_f32_e32 v42, v42, v43
	s_nop 1
	v_add_f32_dpp v42, v42, v42 quad_perm:[1,0,3,2] row_mask:0xf bank_mask:0xf
	s_nop 1
	v_add_f32_dpp v42, v42, v42 quad_perm:[2,3,0,1] row_mask:0xf bank_mask:0xf
	s_nop 1
	v_add_f32_dpp v42, v42, v42 row_half_mirror row_mask:0xf bank_mask:0xf
	s_nop 1
	v_add_f32_dpp v42, v42, v42 row_mirror row_mask:0xf bank_mask:0xf
	s_nop 1
	v_add_f32_dpp v42, v42, v42 row_bcast:15 row_mask:0xa bank_mask:0xf
	s_nop 1
	v_add_f32_dpp v42, v42, v42 row_bcast:31 row_mask:0xc bank_mask:0xf
	s_nop 1
	v_readlane_b32 s100, v42, 63
	s_nop 1
	v_mov_b32_e32 v61, s100
	v_fmac_f32_e32 v48, 0xba800000, v61
	v_fmac_f32_e32 v49, 0xba800000, v61
	v_fmac_f32_e32 v59, 0xba800000, v61
	v_fmac_f32_e32 v58, 0xba800000, v61
	v_mov_b32_e32 v42, v59
	v_mov_b32_e32 v43, v49
	v_mov_b32_e32 v59, v48
	v_pk_mul_f32 v[72:73], v[42:43], v[42:43]
	v_pk_mul_f32 v[48:49], v[58:59], v[58:59]
	v_fmac_f32_e32 v46, 0xba800000, v61
	v_fmac_f32_e32 v47, 0xba800000, v61
	v_fmac_f32_e32 v63, 0xba800000, v61
	v_pk_mov_b32 v[74:75], v[48:49], v[72:73] op_sel:[1,0]
	v_mov_b32_e32 v49, v73
	v_fmac_f32_e32 v62, 0xba800000, v61
	v_mov_b32_e32 v72, v63
	v_mov_b32_e32 v73, v47
	v_mov_b32_e32 v63, v46
	v_pk_add_f32 v[48:49], v[74:75], v[48:49]
	v_pk_mul_f32 v[74:75], v[72:73], v[72:73]
	v_pk_mul_f32 v[46:47], v[62:63], v[62:63]
	v_fmac_f32_e32 v66, 0xba800000, v61
	v_pk_mov_b32 v[76:77], v[46:47], v[74:75] op_sel:[1,0]
	v_mov_b32_e32 v47, v75
	v_pk_add_f32 v[46:47], v[76:77], v[46:47]
	v_fmac_f32_e32 v67, 0xba800000, v61
	v_pk_add_f32 v[46:47], v[46:47], v[46:47] op_sel_hi:[0,1]
	v_fmac_f32_e32 v44, 0xba800000, v61
	v_mul_f32_e32 v46, v66, v66
	v_fmac_f32_e32 v45, 0xba800000, v61
	v_pk_fma_f32 v[74:75], v[66:67], v[66:67], v[46:47] op_sel_hi:[1,1,0]
	v_mul_f32_e32 v46, v44, v44
	v_pk_add_f32 v[48:49], v[48:49], v[48:49] op_sel_hi:[0,1]
	v_pk_fma_f32 v[76:77], v[44:45], v[44:45], v[46:47] op_sel_hi:[1,1,0]
	v_fmac_f32_e32 v60, 0xba800000, v61
	v_fmac_f32_e32 v64, 0xba800000, v61
	v_fmac_f32_e32 v70, 0xba800000, v61
	v_fmac_f32_e32 v68, 0xba800000, v61
	v_mul_f32_e32 v74, v68, v68
	v_mul_f32_e32 v76, v70, v70
	v_mul_f32_e32 v48, v64, v64
	v_mul_f32_e32 v46, v60, v60
	v_pk_add_f32 v[74:75], v[74:75], v[76:77]
	v_pk_add_f32 v[46:47], v[48:49], v[46:47]
	v_mov_b32_e32 v69, v70
	v_pk_add_f32 v[46:47], v[74:75], v[46:47]
	s_nop 0
	v_add_f32_e32 v46, v46, v47
	s_nop 1
	v_add_f32_dpp v46, v46, v46 quad_perm:[1,0,3,2] row_mask:0xf bank_mask:0xf
	s_nop 1
	v_add_f32_dpp v46, v46, v46 quad_perm:[2,3,0,1] row_mask:0xf bank_mask:0xf
	s_nop 1
	v_add_f32_dpp v46, v46, v46 row_half_mirror row_mask:0xf bank_mask:0xf
	s_nop 1
	v_add_f32_dpp v46, v46, v46 row_mirror row_mask:0xf bank_mask:0xf
	s_nop 1
	v_add_f32_dpp v46, v46, v46 row_bcast:15 row_mask:0xa bank_mask:0xf
	s_nop 1
	v_add_f32_dpp v46, v46, v46 row_bcast:31 row_mask:0xc bank_mask:0xf
	s_nop 1
	v_readlane_b32 s100, v46, 63
	s_nop 1
	v_mov_b32_e32 v46, s100
	v_fmamk_f32 v46, v46, 0x3a800000, v56
	v_mul_f32_e32 v47, 0x4f800000, v46
	v_cmp_gt_f32_e32 vcc, s5, v46
	s_nop 1
	v_cndmask_b32_e32 v46, v46, v47, vcc
	v_sqrt_f32_e32 v47, v46
	s_nop 0
	v_add_u32_e32 v48, -1, v47
	v_fma_f32 v49, -v48, v47, v46
	v_cmp_ge_f32_e64 s[0:1], 0, v49
	v_add_u32_e32 v49, 1, v47
	s_nop 0
	v_cndmask_b32_e64 v48, v47, v48, s[0:1]
	v_fma_f32 v47, -v49, v47, v46
	v_cmp_lt_f32_e64 s[0:1], 0, v47
	s_nop 1
	v_cndmask_b32_e64 v47, v48, v49, s[0:1]
	v_mul_f32_e32 v48, 0x37800000, v47
	v_cndmask_b32_e32 v47, v47, v48, vcc
	v_cmp_class_f32_e32 vcc, v46, v57
	s_nop 1
	v_cndmask_b32_e32 v46, v47, v46, vcc
	v_div_scale_f32 v47, s[0:1], v46, v46, 1.0
	v_rcp_f32_e32 v48, v47
	s_nop 0
	v_fma_f32 v49, -v47, v48, 1.0
	v_fmac_f32_e32 v48, v49, v48
	v_div_scale_f32 v49, vcc, 1.0, v46, 1.0
	v_mul_f32_e32 v61, v49, v48
	v_fma_f32 v65, -v47, v61, v49
	v_fmac_f32_e32 v61, v65, v48
	v_fma_f32 v47, -v47, v61, v49
	v_div_fmas_f32 v47, v47, v48, v61
	v_div_fixup_f32 v46, v47, v46, 1.0
	v_pk_mul_f32 v[58:59], v[58:59], v[46:47] op_sel_hi:[1,0]
	v_pk_mul_f32 v[42:43], v[42:43], v[46:47] op_sel_hi:[1,0]
	v_lshl_add_u64 v[48:49], s[2:3], 0, v[32:33]
	v_pk_fma_f32 v[42:43], v[2:3], v[42:43], v[6:7]
	v_pk_fma_f32 v[58:59], v[0:1], v[58:59], v[4:5]
	v_pk_mul_f32 v[44:45], v[44:45], v[46:47] op_sel_hi:[1,0]
	v_cvt_pk_bf16_f32 v58, v58, v59
	v_cvt_pk_bf16_f32 v59, v42, v43
	v_add_co_u32_e32 v42, vcc, s11, v48
	v_pk_fma_f32 v[44:45], v[18:19], v[44:45], v[22:23]
	s_nop 0
	v_addc_co_u32_e32 v43, vcc, 0, v49, vcc
	global_store_dwordx2 v[42:43], v[58:59], off
	v_pk_mul_f32 v[48:49], v[62:63], v[46:47] op_sel_hi:[1,0]
	v_pk_mul_f32 v[58:59], v[72:73], v[46:47] op_sel_hi:[1,0]
	v_pk_fma_f32 v[48:49], v[8:9], v[48:49], v[12:13]
	v_pk_fma_f32 v[58:59], v[10:11], v[58:59], v[14:15]
	v_cvt_pk_bf16_f32 v48, v48, v49
	v_cvt_pk_bf16_f32 v49, v58, v59
	global_store_dwordx2 v[42:43], v[48:49], off offset:512
	v_pk_mul_f32 v[48:49], v[66:67], v[46:47] op_sel_hi:[1,0]
	v_mov_b32_e32 v65, v60
	v_pk_fma_f32 v[48:49], v[16:17], v[48:49], v[20:21]
	s_add_u32 s2, s2, 0x4000
	v_cvt_pk_bf16_f32 v48, v48, v49
	v_cvt_pk_bf16_f32 v49, v44, v45
	v_pk_mul_f32 v[44:45], v[68:69], v[46:47] op_sel_hi:[1,0]
	v_pk_mul_f32 v[46:47], v[64:65], v[46:47] op_sel_hi:[1,0]
	v_pk_fma_f32 v[44:45], v[24:25], v[44:45], v[28:29]
	v_pk_fma_f32 v[46:47], v[26:27], v[46:47], v[30:31]
	s_addc_u32 s3, s3, 0
	v_cvt_pk_bf16_f32 v44, v44, v45
	v_cvt_pk_bf16_f32 v45, v46, v47
	s_add_u32 s6, s6, 0x4000
	global_store_dwordx2 v[42:43], v[48:49], off offset:1024
	global_store_dwordx2 v[42:43], v[44:45], off offset:1536
	s_addc_u32 s7, s7, 0
	s_add_i32 s4, s4, 8
	s_andn2_b64 vcc, exec, s[8:9]
	v_mov_b32_e32 v48, v34
	v_mov_b32_e32 v49, v35
	v_mov_b32_e32 v46, v36
	v_mov_b32_e32 v47, v37
	v_mov_b32_e32 v44, v38
	v_mov_b32_e32 v45, v39
	v_mov_b32_e32 v42, v40
	v_mov_b32_e32 v43, v41
	s_cbranch_vccz .LBB0_445

; __device__ __forceinline__ f32x4 unpack4(u32x2 u) { return (f32x4){__uint_as_float(u.x << 16), __uint_as_float(u.x & 0xffff0000u), __uint_as_float(u.y << 16), __uint_as_float(u.y & 0xffff0000u)}; }
; __device__ __forceinline__ u32x2 pack4(f32x4 v) { u32x2 r; r.x = cvt_pk_bf16(v.x, v.y); r.y = cvt_pk_bf16(v.z, v.w); return r; }
; __device__ __forceinline__ float wave_sum(float v) {
; #pragma unroll
;     for (int o = 1; o < 64; o <<= 1) v += __shfl_xor(v, o);
;     return v;
; }
; __device__ __forceinline__ void ln_pass(const bf16_t* PRE, const float* g, const float* b, float* Hf, bf16_t* HB, int gw, int ngw, int lane, int row_end = MT) {
;     ...
;         f32x4 v[4]; float s = 0.f;
; #pragma unroll
;         for (int j = 0; j < 4; ++j) { v[j] = unpack4(q[j]); s += (v[j].x + v[j].y) + (v[j].z + v[j].w); }
;         const float mean = wave_sum(s) * (1.f / D); float s2 = 0.f;
; #pragma unroll
;         for (int j = 0; j < 4; ++j) { v[j] = v[j] - mean; s2 += (v[j].x * v[j].x + v[j].y * v[j].y) + (v[j].z * v[j].z + v[j].w * v[j].w); }
;         const float rstd = 1.0f / sqrtf(wave_sum(s2) * (1.f / D) + LN_EPS);
; #pragma unroll
;         for (int j = 0; j < 4; ++j) { const f32x4 o = v[j] * rstd * gv[j] + bv[j];
;             if (Hf) *(f32x4*)(Hf + (size_t)row * D + 256 * j + 4 * lane) = o;
;             if (HB) *(u32x2*)(HB + (size_t)row * D + 256 * j + 4 * lane) = pack4(o); }
.LBB0_1280:
	s_waitcnt vmcnt(3)
	v_lshlrev_b32_e32 v59, 16, v49
	v_lshlrev_b32_e32 v58, 16, v48
	v_and_b32_e32 v49, 0xffff0000, v49
	v_and_b32_e32 v48, 0xffff0000, v48
	s_waitcnt vmcnt(2)
	v_lshlrev_b32_e32 v63, 16, v47
	v_lshlrev_b32_e32 v62, 16, v46
	v_and_b32_e32 v47, 0xffff0000, v47
	v_and_b32_e32 v46, 0xffff0000, v46
	v_pk_add_f32 v[60:61], v[58:59], v[48:49]
	v_pk_add_f32 v[64:65], v[62:63], v[46:47]
	v_add_f32_e32 v60, v60, v61
	v_pk_add_f32 v[64:65], v[64:65], v[64:65] op_sel_hi:[0,1]
	s_waitcnt vmcnt(1)
	v_lshlrev_b32_e32 v66, 16, v44
	v_and_b32_e32 v67, 0xffff0000, v44
	v_lshlrev_b32_e32 v44, 16, v45
	v_and_b32_e32 v45, 0xffff0000, v45
	v_add_f32_e32 v61, 0, v60
	v_add_f32_e32 v69, v66, v67
	v_add_f32_e32 v71, v44, v45
	s_waitcnt vmcnt(0)
	v_lshlrev_b32_e32 v68, 16, v42
	v_and_b32_e32 v70, 0xffff0000, v42
	v_lshlrev_b32_e32 v64, 16, v43
	v_and_b32_e32 v60, 0xffff0000, v43
	v_pk_add_f32 v[42:43], v[68:69], v[70:71]
	v_pk_add_f32 v[72:73], v[64:65], v[60:61]
	s_nop 0
	v_pk_add_f32 v[42:43], v[42:43], v[72:73]
	s_nop 0
	v_add_f32_e32 v42, v42, v43
	s_nop 1
	v_add_f32_dpp v42, v42, v42 quad_perm:[1,0,3,2] row_mask:0xf bank_mask:0xf
	s_nop 1
	v_add_f32_dpp v42, v42, v42 quad_perm:[2,3,0,1] row_mask:0xf bank_mask:0xf
	s_nop 1
	v_add_f32_dpp v42, v42, v42 row_half_mirror row_mask:0xf bank_mask:0xf
	s_nop 1
	v_add_f32_dpp v42, v42, v42 row_mirror row_mask:0xf bank_mask:0xf
	s_nop 1
	v_add_f32_dpp v42, v42, v42 row_bcast:15 row_mask:0xa bank_mask:0xf
	s_nop 1
	v_add_f32_dpp v42, v42, v42 row_bcast:31 row_mask:0xc bank_mask:0xf
	s_nop 1
	v_readlane_b32 s100, v42, 63
	s_nop 1
	v_mov_b32_e32 v61, s100
	v_fmac_f32_e32 v48, 0xba800000, v61
	v_fmac_f32_e32 v49, 0xba800000, v61
	v_fmac_f32_e32 v59, 0xba800000, v61
	v_fmac_f32_e32 v58, 0xba800000, v61
	v_mov_b32_e32 v42, v59
	v_mov_b32_e32 v43, v49
	v_mov_b32_e32 v59, v48
	v_pk_mul_f32 v[72:73], v[42:43], v[42:43]
	v_pk_mul_f32 v[48:49], v[58:59], v[58:59]
	v_fmac_f32_e32 v46, 0xba800000, v61
	v_fmac_f32_e32 v47, 0xba800000, v61
	v_fmac_f32_e32 v63, 0xba800000, v61
	v_pk_mov_b32 v[74:75], v[48:49], v[72:73] op_sel:[1,0]
	v_mov_b32_e32 v49, v73
	v_fmac_f32_e32 v62, 0xba800000, v61
	v_mov_b32_e32 v72, v63
	v_mov_b32_e32 v73, v47
	v_mov_b32_e32 v63, v46
	v_pk_add_f32 v[48:49], v[74:75], v[48:49]
	v_pk_mul_f32 v[74:75], v[72:73], v[72:73]
	v_pk_mul_f32 v[46:47], v[62:63], v[62:63]
	v_fmac_f32_e32 v66, 0xba800000, v61
	v_pk_mov_b32 v[76:77], v[46:47], v[74:75] op_sel:[1,0]
	v_mov_b32_e32 v47, v75
	v_pk_add_f32 v[46:47], v[76:77], v[46:47]
	v_fmac_f32_e32 v67, 0xba800000, v61
	v_pk_add_f32 v[46:47], v[46:47], v[46:47] op_sel_hi:[0,1]
	v_fmac_f32_e32 v44, 0xba800000, v61
	v_mul_f32_e32 v46, v66, v66
	v_fmac_f32_e32 v45, 0xba800000, v61
	v_pk_fma_f32 v[74:75], v[66:67], v[66:67], v[46:47] op_sel_hi:[1,1,0]
	v_mul_f32_e32 v46, v44, v44
	v_pk_add_f32 v[48:49], v[48:49], v[48:49] op_sel_hi:[0,1]
	v_pk_fma_f32 v[76:77], v[44:45], v[44:45], v[46:47] op_sel_hi:[1,1,0]
	v_fmac_f32_e32 v60, 0xba800000, v61
	v_fmac_f32_e32 v64, 0xba800000, v61
	v_fmac_f32_e32 v70, 0xba800000, v61
	v_fmac_f32_e32 v68, 0xba800000, v61
	v_mul_f32_e32 v74, v68, v68
	v_mul_f32_e32 v76, v70, v70
	v_mul_f32_e32 v48, v64, v64
	v_mul_f32_e32 v46, v60, v60
	v_pk_add_f32 v[74:75], v[74:75], v[76:77]
	v_pk_add_f32 v[46:47], v[48:49], v[46:47]
	v_mov_b32_e32 v69, v70
	v_pk_add_f32 v[46:47], v[74:75], v[46:47]
	s_nop 0
	v_add_f32_e32 v46, v46, v47
	s_nop 1
	v_add_f32_dpp v46, v46, v46 quad_perm:[1,0,3,2] row_mask:0xf bank_mask:0xf
	s_nop 1
	v_add_f32_dpp v46, v46, v46 quad_perm:[2,3,0,1] row_mask:0xf bank_mask:0xf
	s_nop 1
	v_add_f32_dpp v46, v46, v46 row_half_mirror row_mask:0xf bank_mask:0xf
	s_nop 1
	v_add_f32_dpp v46, v46, v46 row_mirror row_mask:0xf bank_mask:0xf
	s_nop 1
	v_add_f32_dpp v46, v46, v46 row_bcast:15 row_mask:0xa bank_mask:0xf
	s_nop 1
	v_add_f32_dpp v46, v46, v46 row_bcast:31 row_mask:0xc bank_mask:0xf
	s_nop 1
	v_readlane_b32 s100, v46, 63
	s_nop 1
	v_mov_b32_e32 v46, s100
	v_fmamk_f32 v46, v46, 0x3a800000, v56
	v_mul_f32_e32 v47, 0x4f800000, v46
	v_cmp_gt_f32_e32 vcc, s5, v46
	s_nop 1
	v_cndmask_b32_e32 v46, v46, v47, vcc
	v_sqrt_f32_e32 v47, v46
	s_nop 0
	v_add_u32_e32 v48, -1, v47
	v_fma_f32 v49, -v48, v47, v46
	v_cmp_ge_f32_e64 s[0:1], 0, v49
	v_add_u32_e32 v49, 1, v47
	s_nop 0
	v_cndmask_b32_e64 v48, v47, v48, s[0:1]
	v_fma_f32 v47, -v49, v47, v46
	v_cmp_lt_f32_e64 s[0:1], 0, v47
	s_nop 1
	v_cndmask_b32_e64 v47, v48, v49, s[0:1]
	v_mul_f32_e32 v48, 0x37800000, v47
	v_cndmask_b32_e32 v47, v47, v48, vcc
	v_cmp_class_f32_e32 vcc, v46, v57
	s_nop 1
	v_cndmask_b32_e32 v46, v47, v46, vcc
	v_div_scale_f32 v47, s[0:1], v46, v46, 1.0
	v_rcp_f32_e32 v48, v47
	s_nop 0
	v_fma_f32 v49, -v47, v48, 1.0
	v_fmac_f32_e32 v48, v49, v48
	v_div_scale_f32 v49, vcc, 1.0, v46, 1.0
	v_mul_f32_e32 v61, v49, v48
	v_fma_f32 v65, -v47, v61, v49
	v_fmac_f32_e32 v61, v65, v48
	v_fma_f32 v47, -v47, v61, v49
	v_div_fmas_f32 v47, v47, v48, v61
	v_div_fixup_f32 v46, v47, v46, 1.0
	v_pk_mul_f32 v[58:59], v[58:59], v[46:47] op_sel_hi:[1,0]
	v_pk_mul_f32 v[42:43], v[42:43], v[46:47] op_sel_hi:[1,0]
	v_lshl_add_u64 v[48:49], s[2:3], 0, v[32:33]
	v_pk_fma_f32 v[42:43], v[2:3], v[42:43], v[10:11]
	v_pk_fma_f32 v[58:59], v[0:1], v[58:59], v[8:9]
	v_pk_mul_f32 v[44:45], v[44:45], v[46:47] op_sel_hi:[1,0]
	v_cvt_pk_bf16_f32 v58, v58, v59
	v_cvt_pk_bf16_f32 v59, v42, v43
	v_add_co_u32_e32 v42, vcc, s11, v48
	v_pk_fma_f32 v[44:45], v[18:19], v[44:45], v[26:27]
	s_nop 0
	v_addc_co_u32_e32 v43, vcc, 0, v49, vcc
	global_store_dwordx2 v[42:43], v[58:59], off
	v_pk_mul_f32 v[48:49], v[62:63], v[46:47] op_sel_hi:[1,0]
	v_pk_mul_f32 v[58:59], v[72:73], v[46:47] op_sel_hi:[1,0]
	v_pk_fma_f32 v[48:49], v[4:5], v[48:49], v[12:13]
	v_pk_fma_f32 v[58:59], v[6:7], v[58:59], v[14:15]
	v_cvt_pk_bf16_f32 v48, v48, v49
	v_cvt_pk_bf16_f32 v49, v58, v59
	global_store_dwordx2 v[42:43], v[48:49], off offset:512
	v_pk_mul_f32 v[48:49], v[66:67], v[46:47] op_sel_hi:[1,0]
	v_mov_b32_e32 v65, v60
	v_pk_fma_f32 v[48:49], v[16:17], v[48:49], v[24:25]
	s_add_u32 s2, s2, 0x4000
	v_cvt_pk_bf16_f32 v48, v48, v49
	v_cvt_pk_bf16_f32 v49, v44, v45
	v_pk_mul_f32 v[44:45], v[68:69], v[46:47] op_sel_hi:[1,0]
	v_pk_mul_f32 v[46:47], v[64:65], v[46:47] op_sel_hi:[1,0]
	v_pk_fma_f32 v[44:45], v[20:21], v[44:45], v[28:29]
	v_pk_fma_f32 v[46:47], v[22:23], v[46:47], v[30:31]
	s_addc_u32 s3, s3, 0
	v_cvt_pk_bf16_f32 v44, v44, v45
	v_cvt_pk_bf16_f32 v45, v46, v47
	s_add_u32 s6, s6, 0x4000
	global_store_dwordx2 v[42:43], v[48:49], off offset:1024
	global_store_dwordx2 v[42:43], v[44:45], off offset:1536
	s_addc_u32 s7, s7, 0
	s_add_i32 s4, s4, 8
	s_andn2_b64 vcc, exec, s[8:9]
	v_mov_b32_e32 v48, v34
	v_mov_b32_e32 v49, v35
	v_mov_b32_e32 v46, v36
	v_mov_b32_e32 v47, v37
	v_mov_b32_e32 v44, v38
	v_mov_b32_e32 v45, v39
	v_mov_b32_e32 v42, v40
	v_mov_b32_e32 v43, v41
	s_cbranch_vccz .LBB0_1283

; __device__ __forceinline__ f32x4 unpack4(u32x2 u) { return (f32x4){__uint_as_float(u.x << 16), __uint_as_float(u.x & 0xffff0000u), __uint_as_float(u.y << 16), __uint_as_float(u.y & 0xffff0000u)}; }
; __device__ __forceinline__ u32x2 pack4(f32x4 v) { u32x2 r; r.x = cvt_pk_bf16(v.x, v.y); r.y = cvt_pk_bf16(v.z, v.w); return r; }
; __device__ __forceinline__ float wave_sum(float v) {
; #pragma unroll
;     for (int o = 1; o < 64; o <<= 1) v += __shfl_xor(v, o);
;     return v;
; }
; __device__ __forceinline__ void ln_pass(const bf16_t* PRE, const float* g, const float* b, float* Hf, bf16_t* HB, int gw, int ngw, int lane, int row_end = MT) {
;     ...
;         f32x4 v[4]; float s = 0.f;
; #pragma unroll
;         for (int j = 0; j < 4; ++j) { v[j] = unpack4(q[j]); s += (v[j].x + v[j].y) + (v[j].z + v[j].w); }
;         const float mean = wave_sum(s) * (1.f / D); float s2 = 0.f;
; #pragma unroll
;         for (int j = 0; j < 4; ++j) { v[j] = v[j] - mean; s2 += (v[j].x * v[j].x + v[j].y * v[j].y) + (v[j].z * v[j].z + v[j].w * v[j].w); }
;         const float rstd = 1.0f / sqrtf(wave_sum(s2) * (1.f / D) + LN_EPS);
; #pragma unroll
;         for (int j = 0; j < 4; ++j) { const f32x4 o = v[j] * rstd * gv[j] + bv[j];
;             if (Hf) *(f32x4*)(Hf + (size_t)row * D + 256 * j + 4 * lane) = o;
;             if (HB) *(u32x2*)(HB + (size_t)row * D + 256 * j + 4 * lane) = pack4(o); }
.LBB0_1953:
	s_waitcnt vmcnt(3)
	v_lshlrev_b32_e32 v63, 16, v45
	v_lshlrev_b32_e32 v62, 16, v44
	v_and_b32_e32 v61, 0xffff0000, v45
	v_and_b32_e32 v60, 0xffff0000, v44
	s_waitcnt vmcnt(2)
	v_lshlrev_b32_e32 v59, 16, v51
	v_lshlrev_b32_e32 v58, 16, v50
	v_and_b32_e32 v57, 0xffff0000, v51
	v_and_b32_e32 v56, 0xffff0000, v50
	v_pk_add_f32 v[44:45], v[62:63], v[60:61]
	v_pk_add_f32 v[50:51], v[58:59], v[56:57]
	v_add_f32_e32 v44, v44, v45
	v_pk_add_f32 v[50:51], v[50:51], v[50:51] op_sel_hi:[0,1]
	s_waitcnt vmcnt(1)
	v_lshlrev_b32_e32 v54, 16, v48
	v_and_b32_e32 v55, 0xffff0000, v48
	v_lshlrev_b32_e32 v52, 16, v49
	v_and_b32_e32 v53, 0xffff0000, v49
	v_add_f32_e32 v45, 0, v44
	v_add_f32_e32 v49, v54, v55
	v_add_f32_e32 v65, v52, v53
	s_waitcnt vmcnt(0)
	v_lshlrev_b32_e32 v48, 16, v46
	v_and_b32_e32 v64, 0xffff0000, v46
	v_lshlrev_b32_e32 v50, 16, v47
	v_and_b32_e32 v44, 0xffff0000, v47
	v_pk_add_f32 v[46:47], v[48:49], v[64:65]
	v_pk_add_f32 v[74:75], v[50:51], v[44:45]
	s_andn2_b64 vcc, exec, s[4:5]
	v_pk_add_f32 v[46:47], v[46:47], v[74:75]
	s_nop 0
	v_add_f32_e32 v45, v46, v47
	s_nop 1
	v_add_f32_dpp v45, v45, v45 quad_perm:[1,0,3,2] row_mask:0xf bank_mask:0xf
	s_nop 1
	v_add_f32_dpp v45, v45, v45 quad_perm:[2,3,0,1] row_mask:0xf bank_mask:0xf
	s_nop 1
	v_add_f32_dpp v45, v45, v45 row_half_mirror row_mask:0xf bank_mask:0xf
	s_nop 1
	v_add_f32_dpp v45, v45, v45 row_mirror row_mask:0xf bank_mask:0xf
	s_nop 1
	v_add_f32_dpp v45, v45, v45 row_bcast:15 row_mask:0xa bank_mask:0xf
	s_nop 1
	v_add_f32_dpp v45, v45, v45 row_bcast:31 row_mask:0xc bank_mask:0xf
	s_nop 1
	v_readlane_b32 s100, v45, 63
	s_nop 1
	v_mov_b32_e32 v45, s100
	v_fmac_f32_e32 v61, 0xba800000, v45
	v_fmac_f32_e32 v60, 0xba800000, v45
	v_fmac_f32_e32 v63, 0xba800000, v45
	v_fmac_f32_e32 v62, 0xba800000, v45
	v_mul_f32_e32 v46, v60, v60
	v_mul_f32_e32 v47, v61, v61
	v_fmac_f32_e32 v46, v62, v62
	v_fmac_f32_e32 v47, v63, v63
	v_fmac_f32_e32 v57, 0xba800000, v45
	v_fmac_f32_e32 v56, 0xba800000, v45
	v_add_f32_e32 v46, v46, v47
	v_fmac_f32_e32 v59, 0xba800000, v45
	v_fmac_f32_e32 v58, 0xba800000, v45
	v_mul_f32_e32 v47, v56, v56
	v_mul_f32_e32 v49, v57, v57
	v_fmac_f32_e32 v47, v58, v58
	v_fmac_f32_e32 v49, v59, v59
	v_add_f32_e32 v47, v47, v49
	v_fmac_f32_e32 v53, 0xba800000, v45
	v_fmac_f32_e32 v55, 0xba800000, v45
	v_add_f32_e32 v46, v46, v47
	v_fmac_f32_e32 v52, 0xba800000, v45
	v_fmac_f32_e32 v54, 0xba800000, v45
	v_mul_f32_e32 v47, v55, v55
	v_mul_f32_e32 v49, v53, v53
	v_fmac_f32_e32 v47, v54, v54
	v_fmac_f32_e32 v49, v52, v52
	v_add_f32_e32 v47, v47, v49
	v_fmac_f32_e32 v44, 0xba800000, v45
	v_fmac_f32_e32 v64, 0xba800000, v45
	v_add_f32_e32 v46, v47, v46
	v_fmac_f32_e32 v50, 0xba800000, v45
	v_fmac_f32_e32 v48, 0xba800000, v45
	v_mul_f32_e32 v45, v64, v64
	v_mul_f32_e32 v47, v44, v44
	v_fmac_f32_e32 v45, v48, v48
	v_fmac_f32_e32 v47, v50, v50
	v_add_f32_e32 v45, v45, v47
	v_add_f32_e32 v45, v45, v46
	s_nop 1
	v_add_f32_dpp v45, v45, v45 quad_perm:[1,0,3,2] row_mask:0xf bank_mask:0xf
	s_nop 1
	v_add_f32_dpp v45, v45, v45 quad_perm:[2,3,0,1] row_mask:0xf bank_mask:0xf
	s_nop 1
	v_add_f32_dpp v45, v45, v45 row_half_mirror row_mask:0xf bank_mask:0xf
	s_nop 1
	v_add_f32_dpp v45, v45, v45 row_mirror row_mask:0xf bank_mask:0xf
	s_nop 1
	v_add_f32_dpp v45, v45, v45 row_bcast:15 row_mask:0xa bank_mask:0xf
	s_nop 1
	v_add_f32_dpp v45, v45, v45 row_bcast:31 row_mask:0xc bank_mask:0xf
	s_nop 1
	v_readlane_b32 s100, v45, 63
	s_nop 1
	v_mov_b32_e32 v45, s100
	v_mov_b32_e32 v46, 0
	s_cbranch_vccnz .LBB0_1950
	s_waitcnt lgkmcnt(0)
	v_add_f32_e32 v45, v45, v46
	v_fmamk_f32 v45, v45, 0x3a800000, v72
	v_mul_f32_e32 v46, 0x4f800000, v45
	v_cmp_gt_f32_e32 vcc, s3, v45
	v_mov_b32_e32 v47, v60
	v_mov_b32_e32 v75, v56
	v_cndmask_b32_e32 v45, v45, v46, vcc
	v_sqrt_f32_e32 v49, v45
	v_mov_b32_e32 v74, v58
	v_mov_b32_e32 v46, v62
	v_add_u32_e32 v51, -1, v49
	v_fma_f32 v60, -v51, v49, v45
	v_cmp_ge_f32_e64 s[0:1], 0, v60
	v_add_u32_e32 v60, 1, v49
	s_nop 0
	v_cndmask_b32_e64 v51, v49, v51, s[0:1]
	v_fma_f32 v49, -v60, v49, v45
	v_cmp_lt_f32_e64 s[0:1], 0, v49
	s_nop 1
	v_cndmask_b32_e64 v49, v51, v60, s[0:1]
	v_mul_f32_e32 v51, 0x37800000, v49
	v_cndmask_b32_e32 v49, v49, v51, vcc
	v_cmp_class_f32_e32 vcc, v45, v73
	s_nop 1
	v_cndmask_b32_e32 v45, v49, v45, vcc
	v_div_scale_f32 v51, s[0:1], v45, v45, 1.0
	v_rcp_f32_e32 v60, v51
	v_mov_b32_e32 v49, v64
	v_fma_f32 v56, -v51, v60, 1.0
	v_fmac_f32_e32 v60, v56, v60
	v_div_scale_f32 v56, vcc, 1.0, v45, 1.0
	v_mul_f32_e32 v58, v56, v60
	v_fma_f32 v62, -v51, v58, v56
	v_fmac_f32_e32 v58, v62, v60
	v_fma_f32 v51, -v51, v58, v56
	v_div_fmas_f32 v51, v51, v60, v58
	v_div_fixup_f32 v64, v51, v45, 1.0
	v_mov_b32_e32 v60, v63
	v_pk_mul_f32 v[46:47], v[46:47], v[64:65] op_sel_hi:[1,0]
	v_pk_mul_f32 v[60:61], v[60:61], v[64:65] op_sel_hi:[1,0]
	v_mov_b32_e32 v56, v59
	v_pk_fma_f32 v[62:63], v[2:3], v[60:61], v[10:11]
	v_pk_fma_f32 v[60:61], v[0:1], v[46:47], v[8:9]
	v_pk_mul_f32 v[46:47], v[74:75], v[64:65] op_sel_hi:[1,0]
	v_pk_mul_f32 v[56:57], v[56:57], v[64:65] op_sel_hi:[1,0]
	v_mov_b32_e32 v51, v44
	v_pk_fma_f32 v[58:59], v[6:7], v[56:57], v[14:15]
	v_pk_fma_f32 v[56:57], v[4:5], v[46:47], v[12:13]
	v_pk_mul_f32 v[46:47], v[54:55], v[64:65] op_sel_hi:[1,0]
	v_pk_mul_f32 v[52:53], v[52:53], v[64:65] op_sel_hi:[1,0]
	v_pk_mul_f32 v[48:49], v[48:49], v[64:65] op_sel_hi:[1,0]
	v_pk_mul_f32 v[44:45], v[50:51], v[64:65] op_sel_hi:[1,0]
	v_pk_fma_f32 v[54:55], v[18:19], v[52:53], v[26:27]
	v_pk_fma_f32 v[52:53], v[16:17], v[46:47], v[24:25]
	v_pk_fma_f32 v[46:47], v[22:23], v[44:45], v[30:31]
	v_pk_fma_f32 v[44:45], v[20:21], v[48:49], v[28:29]
	global_store_dwordx4 v[34:35], v[60:63], off
	global_store_dwordx4 v[34:35], v[56:59], off offset:1024
	global_store_dwordx4 v[34:35], v[52:55], off offset:2048
	global_store_dwordx4 v[34:35], v[44:47], off offset:3072
	s_branch .LBB0_1950
